# P1 K-loop: s_setprio roles swapped (loader segments at priority 1, MFMA segments at 0)
# speedup vs baseline: 1.0042x; 1.0005x over previous
; #define PG8_STAGE(bufoff, gbase, voff) do { _Pragma("unroll") for (int _i = 0; _i < 2; ++_i) \
;         __builtin_amdgcn_global_load_lds((const unsigned*)((const char*)(gbase) + (voff)[_i]), (PG8_LAS unsigned*)(lds + (bufoff) + ldsw + _i * 8192), 16, 0, 0); } while (0)
; #define PG8_LDA(dst, b, h) do { _Pragma("unroll") for (int m = 0; m < 4; ++m) _Pragma("unroll") for (int k = 0; k < 2; ++k) dst[m][k] = *(const PG8_LAS bf16x8*)(lds + PG8_SA(b, h) + aoff + m * 2048 + k * 1024); } while (0)
; #define PG8_LDB(dst, b, h) do { _Pragma("unroll") for (int n = 0; n < 2; ++n) _Pragma("unroll") for (int k = 0; k < 2; ++k) dst[n][k] = *(const PG8_LAS bf16x8*)(lds + PG8_SB(b, h) + boff + n * 2048 + k * 1024); } while (0)
; #define PG8_MMA(ai, bj, At, Bt) do { __builtin_amdgcn_s_setprio(1); _Pragma("unroll") for (int m = 0; m < 4; ++m) _Pragma("unroll") for (int n = 0; n < 2; ++n) _Pragma("unroll") for (int k = 0; k < 2; ++k) \
;         acc[ai][bj][m][n] = __builtin_amdgcn_mfma_f32_16x16x32_bf16(Bt[n][k], At[m][k], acc[ai][bj][m][n], 0, 0, 0); __builtin_amdgcn_s_setprio(0); } while (0)
; #define PG8_WAIT_V(n) asm volatile("s_waitcnt vmcnt(" #n ")" ::: "memory")
; #define PG8_WAIT_L(n) asm volatile("s_waitcnt lgkmcnt(" #n ")" ::: "memory")
; #define PG8_BAR __builtin_amdgcn_s_barrier()
; #define PG8_SCHED __builtin_amdgcn_sched_barrier(0)
; template <class Epi, class Sched>
; __device__ __forceinline__ void gemm_phase(PG8_LAS unsigned char* lds, const Gemm g, const Sched& S, const Epi& E) {
;     ...
;             PG8_LDB(B0, 0, 0); PG8_LDB(B1, 0, 1); PG8_SCHED; PG8_LDA(At, 0, 0); PG8_STAGE(PG8_SA(1, 1), a1 + hstepA, voffA);
;             PG8_WAIT_V(8); PG8_WAIT_L(0); PG8_BAR; PG8_MMA(0, 0, At, B0); PG8_MMA(0, 1, At, B1); PG8_BAR; PG8_SCHED;
;             PG8_LDA(At, 0, 1); PG8_STAGE(PG8_SB(0, 0), b2, voffB); PG8_STAGE(PG8_SB(0, 1), b2 + hstepB, voffB); PG8_STAGE(PG8_SA(0, 0), a2, voffA);
;             PG8_WAIT_V(8); PG8_WAIT_L(0); PG8_BAR; PG8_MMA(1, 0, At, B0); PG8_MMA(1, 1, At, B1); PG8_BAR; PG8_SCHED;
.LBB0_161:
	s_add_u32 s41, s6, 0xfffc0080
	s_addc_u32 s49, s7, -1
	s_add_i32 s57, 0, 0x10000
	s_cmp_eq_u32 s39, 12
	s_cselect_b32 s55, s43, s49
	s_cselect_b32 s54, s42, s41
	s_cselect_b32 s53, s45, s18
	s_cselect_b32 s52, s44, s2
	s_add_i32 s41, 0, 0x14000
	v_add_u32_e32 v142, s57, v168
	v_add_u32_e32 v164, s41, v168
	ds_read_b128 v[130:133], v142
	ds_read_b128 v[134:137], v142 offset:1024
	ds_read_b128 v[138:141], v142 offset:2048
	ds_read_b128 v[142:145], v142 offset:3072
	ds_read_b128 v[156:159], v164
	ds_read_b128 v[160:163], v164 offset:1024
	ds_read_b128 v[170:173], v164 offset:2048
	ds_read_b128 v[174:177], v164 offset:3072
	v_lshl_add_u64 v[164:165], s[6:7], 0, v[152:153]
	s_add_i32 m0, s60, 0xc000
	ds_read_b128 v[178:181], v169
	ds_read_b128 v[182:185], v169 offset:1024
	ds_read_b128 v[186:189], v169 offset:2048
	ds_read_b128 v[190:193], v169 offset:3072
	ds_read_b128 v[202:205], v169 offset:4096
	ds_read_b128 v[206:209], v169 offset:5120
	ds_read_b128 v[210:213], v169 offset:6144
	ds_read_b128 v[214:217], v169 offset:7168
	global_load_lds_dwordx4 v[164:165], off
	v_lshl_add_u64 v[164:165], s[6:7], 0, v[154:155]
	s_add_i32 m0, s60, 0xe000
	s_nop 0
	global_load_lds_dwordx4 v[164:165], off
	s_waitcnt vmcnt(8)
	s_waitcnt lgkmcnt(0)
	s_barrier
	s_setprio 0
	s_waitcnt lgkmcnt(0)
	v_mfma_f32_16x16x32_bf16 v[126:129], v[130:133], v[178:181], v[126:129]
	v_mfma_f32_16x16x32_bf16 v[122:125], v[138:141], v[178:181], v[122:125]
	v_mfma_f32_16x16x32_bf16 v[118:121], v[130:133], v[186:189], v[118:121]
	v_mfma_f32_16x16x32_bf16 v[114:117], v[138:141], v[186:189], v[114:117]
	v_mfma_f32_16x16x32_bf16 v[110:113], v[130:133], v[202:205], v[110:113]
	v_mfma_f32_16x16x32_bf16 v[106:109], v[138:141], v[202:205], v[106:109]
	v_mfma_f32_16x16x32_bf16 v[102:105], v[130:133], v[210:213], v[102:105]
	v_mfma_f32_16x16x32_bf16 v[98:101], v[138:141], v[210:213], v[98:101]
	v_mfma_f32_16x16x32_bf16 v[126:129], v[134:137], v[182:185], v[126:129]
	v_mfma_f32_16x16x32_bf16 v[122:125], v[142:145], v[182:185], v[122:125]
	v_mfma_f32_16x16x32_bf16 v[118:121], v[134:137], v[190:193], v[118:121]
	v_mfma_f32_16x16x32_bf16 v[114:117], v[142:145], v[190:193], v[114:117]
	v_mfma_f32_16x16x32_bf16 v[110:113], v[134:137], v[206:209], v[110:113]
	v_mfma_f32_16x16x32_bf16 v[106:109], v[142:145], v[206:209], v[106:109]
	v_mfma_f32_16x16x32_bf16 v[102:105], v[134:137], v[214:217], v[102:105]
	v_mfma_f32_16x16x32_bf16 v[98:101], v[142:145], v[214:217], v[98:101]
	s_setprio 1
	s_setprio 0
	v_mfma_f32_16x16x32_bf16 v[62:65], v[156:159], v[178:181], v[62:65]
	v_mfma_f32_16x16x32_bf16 v[58:61], v[170:173], v[178:181], v[58:61]
	v_mfma_f32_16x16x32_bf16 v[54:57], v[156:159], v[186:189], v[54:57]
	v_mfma_f32_16x16x32_bf16 v[50:53], v[170:173], v[186:189], v[50:53]
	v_mfma_f32_16x16x32_bf16 v[46:49], v[156:159], v[202:205], v[46:49]
	v_mfma_f32_16x16x32_bf16 v[42:45], v[170:173], v[202:205], v[42:45]
	v_mfma_f32_16x16x32_bf16 v[38:41], v[156:159], v[210:213], v[38:41]
	v_mfma_f32_16x16x32_bf16 v[34:37], v[170:173], v[210:213], v[34:37]
	v_mfma_f32_16x16x32_bf16 v[62:65], v[160:163], v[182:185], v[62:65]
	v_mfma_f32_16x16x32_bf16 v[58:61], v[174:177], v[182:185], v[58:61]
	v_mfma_f32_16x16x32_bf16 v[54:57], v[160:163], v[190:193], v[54:57]
	v_mfma_f32_16x16x32_bf16 v[50:53], v[174:177], v[190:193], v[50:53]
	v_mfma_f32_16x16x32_bf16 v[46:49], v[160:163], v[206:209], v[46:49]
	v_mfma_f32_16x16x32_bf16 v[42:45], v[174:177], v[206:209], v[42:45]
	v_mfma_f32_16x16x32_bf16 v[38:41], v[160:163], v[214:217], v[38:41]
	v_mfma_f32_16x16x32_bf16 v[34:37], v[174:177], v[214:217], v[34:37]
	s_setprio 1
	s_barrier
	s_add_i32 s49, s57, s59
	v_lshl_add_u64 v[164:165], s[52:53], 0, v[0:1]
	s_mov_b32 m0, s49
	ds_read_b128 v[178:181], v169 offset:16384
	ds_read_b128 v[182:185], v169 offset:17408
	ds_read_b128 v[186:189], v169 offset:18432
	ds_read_b128 v[190:193], v169 offset:19456
	ds_read_b128 v[202:205], v169 offset:20480
	ds_read_b128 v[206:209], v169 offset:21504
	ds_read_b128 v[210:213], v169 offset:22528
	ds_read_b128 v[214:217], v169 offset:23552
	global_load_lds_dwordx4 v[164:165], off
	s_add_i32 m0, s49, 0x2000
	s_add_u32 s74, s52, 0x10000
	v_lshl_add_u64 v[194:195], s[52:53], 0, v[150:151]
	s_addc_u32 s75, s53, 0
	s_add_i32 s41, s41, s59
	global_load_lds_dwordx4 v[194:195], off
	v_lshl_add_u64 v[196:197], s[74:75], 0, v[0:1]
	s_mov_b32 m0, s41
	v_lshl_add_u64 v[218:219], s[54:55], 0, v[148:149]
	global_load_lds_dwordx4 v[196:197], off
	v_lshl_add_u64 v[196:197], s[74:75], 0, v[150:151]
	s_add_i32 m0, s41, 0x2000
	s_nop 0
	global_load_lds_dwordx4 v[196:197], off
	v_lshl_add_u64 v[196:197], s[54:55], 0, v[146:147]
	s_mov_b32 m0, s60
	s_nop 0
	global_load_lds_dwordx4 v[196:197], off
	s_mov_b32 m0, s61
	s_nop 0
	global_load_lds_dwordx4 v[218:219], off
	s_waitcnt vmcnt(8)
	s_waitcnt lgkmcnt(0)
	s_barrier
; #define PG8_STAGE(bufoff, gbase, voff) do { _Pragma("unroll") for (int _i = 0; _i < 2; ++_i) \
;         __builtin_amdgcn_global_load_lds((const unsigned*)((const char*)(gbase) + (voff)[_i]), (PG8_LAS unsigned*)(lds + (bufoff) + ldsw + _i * 8192), 16, 0, 0); } while (0)
; #define PG8_LDA(dst, b, h) do { _Pragma("unroll") for (int m = 0; m < 4; ++m) _Pragma("unroll") for (int k = 0; k < 2; ++k) dst[m][k] = *(const PG8_LAS bf16x8*)(lds + PG8_SA(b, h) + aoff + m * 2048 + k * 1024); } while (0)
; #define PG8_LDB(dst, b, h) do { _Pragma("unroll") for (int n = 0; n < 2; ++n) _Pragma("unroll") for (int k = 0; k < 2; ++k) dst[n][k] = *(const PG8_LAS bf16x8*)(lds + PG8_SB(b, h) + boff + n * 2048 + k * 1024); } while (0)
; #define PG8_MMA(ai, bj, At, Bt) do { __builtin_amdgcn_s_setprio(1); _Pragma("unroll") for (int m = 0; m < 4; ++m) _Pragma("unroll") for (int n = 0; n < 2; ++n) _Pragma("unroll") for (int k = 0; k < 2; ++k) \
;         acc[ai][bj][m][n] = __builtin_amdgcn_mfma_f32_16x16x32_bf16(Bt[n][k], At[m][k], acc[ai][bj][m][n], 0, 0, 0); __builtin_amdgcn_s_setprio(0); } while (0)
; #define PG8_WAIT_V(n) asm volatile("s_waitcnt vmcnt(" #n ")" ::: "memory")
; #define PG8_WAIT_L(n) asm volatile("s_waitcnt lgkmcnt(" #n ")" ::: "memory")
; #define PG8_BAR __builtin_amdgcn_s_barrier()
; #define PG8_SCHED __builtin_amdgcn_sched_barrier(0)
; template <class Epi, class Sched>
; __device__ __forceinline__ void gemm_phase(PG8_LAS unsigned char* lds, const Gemm g, const Sched& S, const Epi& E) {
;     ...
;             PG8_WAIT_V(8); PG8_WAIT_L(0); PG8_BAR; PG8_MMA(1, 0, At, B0); PG8_MMA(1, 1, At, B1); PG8_BAR; PG8_SCHED;
;             PG8_LDB(B0, 1, 0); PG8_LDB(B1, 1, 1); PG8_SCHED; PG8_LDA(At, 1, 0); PG8_STAGE(PG8_SA(0, 1), a2 + hstepA, voffA);
;             PG8_WAIT_V(8); PG8_WAIT_L(0); PG8_BAR; PG8_MMA(0, 0, At, B0); PG8_MMA(0, 1, At, B1); PG8_BAR; PG8_SCHED;
	s_setprio 0
	s_waitcnt lgkmcnt(0)
	v_mfma_f32_16x16x32_bf16 v[94:97], v[130:133], v[178:181], v[94:97]
	v_mfma_f32_16x16x32_bf16 v[90:93], v[138:141], v[178:181], v[90:93]
	v_mfma_f32_16x16x32_bf16 v[86:89], v[130:133], v[186:189], v[86:89]
	v_mfma_f32_16x16x32_bf16 v[82:85], v[138:141], v[186:189], v[82:85]
	v_mfma_f32_16x16x32_bf16 v[78:81], v[130:133], v[202:205], v[78:81]
	v_mfma_f32_16x16x32_bf16 v[74:77], v[138:141], v[202:205], v[74:77]
	v_mfma_f32_16x16x32_bf16 v[70:73], v[130:133], v[210:213], v[70:73]
	v_mfma_f32_16x16x32_bf16 v[66:69], v[138:141], v[210:213], v[66:69]
	v_mfma_f32_16x16x32_bf16 v[94:97], v[134:137], v[182:185], v[94:97]
	v_mfma_f32_16x16x32_bf16 v[90:93], v[142:145], v[182:185], v[90:93]
	v_mfma_f32_16x16x32_bf16 v[86:89], v[134:137], v[190:193], v[86:89]
	v_mfma_f32_16x16x32_bf16 v[82:85], v[142:145], v[190:193], v[82:85]
	v_mfma_f32_16x16x32_bf16 v[78:81], v[134:137], v[206:209], v[78:81]
	v_mfma_f32_16x16x32_bf16 v[74:77], v[142:145], v[206:209], v[74:77]
	v_mfma_f32_16x16x32_bf16 v[70:73], v[134:137], v[214:217], v[70:73]
	v_mfma_f32_16x16x32_bf16 v[66:69], v[142:145], v[214:217], v[66:69]
	s_setprio 1
	s_setprio 0
	v_mfma_f32_16x16x32_bf16 v[30:33], v[156:159], v[178:181], v[30:33]
	v_mfma_f32_16x16x32_bf16 v[26:29], v[170:173], v[178:181], v[26:29]
	v_mfma_f32_16x16x32_bf16 v[22:25], v[156:159], v[186:189], v[22:25]
	v_mfma_f32_16x16x32_bf16 v[18:21], v[170:173], v[186:189], v[18:21]
	v_mfma_f32_16x16x32_bf16 v[14:17], v[156:159], v[202:205], v[14:17]
	v_mfma_f32_16x16x32_bf16 v[10:13], v[170:173], v[202:205], v[10:13]
	v_mfma_f32_16x16x32_bf16 v[6:9], v[156:159], v[210:213], v[6:9]
	v_mfma_f32_16x16x32_bf16 v[2:5], v[170:173], v[210:213], v[2:5]
	v_mfma_f32_16x16x32_bf16 v[30:33], v[160:163], v[182:185], v[30:33]
	v_mfma_f32_16x16x32_bf16 v[26:29], v[174:177], v[182:185], v[26:29]
	v_mfma_f32_16x16x32_bf16 v[22:25], v[160:163], v[190:193], v[22:25]
	v_mfma_f32_16x16x32_bf16 v[18:21], v[174:177], v[190:193], v[18:21]
	v_mfma_f32_16x16x32_bf16 v[14:17], v[160:163], v[206:209], v[14:17]
	v_mfma_f32_16x16x32_bf16 v[10:13], v[174:177], v[206:209], v[10:13]
	v_mfma_f32_16x16x32_bf16 v[6:9], v[160:163], v[214:217], v[6:9]
	v_mfma_f32_16x16x32_bf16 v[2:5], v[174:177], v[214:217], v[2:5]
	s_setprio 1
	s_barrier
	s_add_i32 s41, 0, 0x18000
	s_add_i32 s49, 0, 0x1c000
	v_add_u32_e32 v142, s41, v168
	v_add_u32_e32 v174, s49, v168
	ds_read_b128 v[130:133], v142
	ds_read_b128 v[134:137], v142 offset:1024
	ds_read_b128 v[138:141], v142 offset:2048
	ds_read_b128 v[142:145], v142 offset:3072
	ds_read_b128 v[156:159], v174
	ds_read_b128 v[160:163], v174 offset:1024
	ds_read_b128 v[170:173], v174 offset:2048
	ds_read_b128 v[174:177], v174 offset:3072
	s_add_u32 s54, s54, 0x40000
	s_addc_u32 s55, s55, 0
	s_mov_b32 m0, s62
	v_lshl_add_u64 v[220:221], s[54:55], 0, v[146:147]
	ds_read_b128 v[178:181], v169 offset:32768
	ds_read_b128 v[182:185], v169 offset:33792
	ds_read_b128 v[186:189], v169 offset:34816
	ds_read_b128 v[190:193], v169 offset:35840
	ds_read_b128 v[202:205], v169 offset:36864
	ds_read_b128 v[206:209], v169 offset:37888
	ds_read_b128 v[210:213], v169 offset:38912
	ds_read_b128 v[214:217], v169 offset:39936
	global_load_lds_dwordx4 v[220:221], off
	v_lshl_add_u64 v[220:221], s[54:55], 0, v[148:149]
	s_mov_b32 m0, s63
	s_nop 0
	global_load_lds_dwordx4 v[220:221], off
	s_waitcnt vmcnt(8)
	s_waitcnt lgkmcnt(0)
	s_barrier
	s_setprio 0
	s_waitcnt lgkmcnt(0)
	v_mfma_f32_16x16x32_bf16 v[126:129], v[130:133], v[178:181], v[126:129]
	v_mfma_f32_16x16x32_bf16 v[122:125], v[138:141], v[178:181], v[122:125]
	v_mfma_f32_16x16x32_bf16 v[118:121], v[130:133], v[186:189], v[118:121]
	v_mfma_f32_16x16x32_bf16 v[114:117], v[138:141], v[186:189], v[114:117]
	v_mfma_f32_16x16x32_bf16 v[110:113], v[130:133], v[202:205], v[110:113]
	v_mfma_f32_16x16x32_bf16 v[106:109], v[138:141], v[202:205], v[106:109]
	v_mfma_f32_16x16x32_bf16 v[102:105], v[130:133], v[210:213], v[102:105]
	v_mfma_f32_16x16x32_bf16 v[98:101], v[138:141], v[210:213], v[98:101]
	v_mfma_f32_16x16x32_bf16 v[126:129], v[134:137], v[182:185], v[126:129]
	v_mfma_f32_16x16x32_bf16 v[122:125], v[142:145], v[182:185], v[122:125]
	v_mfma_f32_16x16x32_bf16 v[118:121], v[134:137], v[190:193], v[118:121]
	v_mfma_f32_16x16x32_bf16 v[114:117], v[142:145], v[190:193], v[114:117]
	v_mfma_f32_16x16x32_bf16 v[110:113], v[134:137], v[206:209], v[110:113]
	v_mfma_f32_16x16x32_bf16 v[106:109], v[142:145], v[206:209], v[106:109]
	v_mfma_f32_16x16x32_bf16 v[102:105], v[134:137], v[214:217], v[102:105]
	v_mfma_f32_16x16x32_bf16 v[98:101], v[142:145], v[214:217], v[98:101]
	s_setprio 1
	s_setprio 0
	v_mfma_f32_16x16x32_bf16 v[62:65], v[156:159], v[178:181], v[62:65]
	v_mfma_f32_16x16x32_bf16 v[58:61], v[170:173], v[178:181], v[58:61]
	v_mfma_f32_16x16x32_bf16 v[54:57], v[156:159], v[186:189], v[54:57]
	v_mfma_f32_16x16x32_bf16 v[50:53], v[170:173], v[186:189], v[50:53]
	v_mfma_f32_16x16x32_bf16 v[46:49], v[156:159], v[202:205], v[46:49]
	v_mfma_f32_16x16x32_bf16 v[42:45], v[170:173], v[202:205], v[42:45]
	v_mfma_f32_16x16x32_bf16 v[38:41], v[156:159], v[210:213], v[38:41]
	v_mfma_f32_16x16x32_bf16 v[34:37], v[170:173], v[210:213], v[34:37]
	v_mfma_f32_16x16x32_bf16 v[62:65], v[160:163], v[182:185], v[62:65]
	v_mfma_f32_16x16x32_bf16 v[58:61], v[174:177], v[182:185], v[58:61]
	v_mfma_f32_16x16x32_bf16 v[54:57], v[160:163], v[190:193], v[54:57]
	v_mfma_f32_16x16x32_bf16 v[50:53], v[174:177], v[190:193], v[50:53]
	v_mfma_f32_16x16x32_bf16 v[46:49], v[160:163], v[206:209], v[46:49]
	v_mfma_f32_16x16x32_bf16 v[42:45], v[174:177], v[206:209], v[42:45]
	v_mfma_f32_16x16x32_bf16 v[38:41], v[160:163], v[214:217], v[38:41]
	v_mfma_f32_16x16x32_bf16 v[34:37], v[174:177], v[214:217], v[34:37]
	s_setprio 1
	s_barrier
; #define PG8_STAGE(bufoff, gbase, voff) do { _Pragma("unroll") for (int _i = 0; _i < 2; ++_i) \
;         __builtin_amdgcn_global_load_lds((const unsigned*)((const char*)(gbase) + (voff)[_i]), (PG8_LAS unsigned*)(lds + (bufoff) + ldsw + _i * 8192), 16, 0, 0); } while (0)
; #define PG8_LDA(dst, b, h) do { _Pragma("unroll") for (int m = 0; m < 4; ++m) _Pragma("unroll") for (int k = 0; k < 2; ++k) dst[m][k] = *(const PG8_LAS bf16x8*)(lds + PG8_SA(b, h) + aoff + m * 2048 + k * 1024); } while (0)
; #define PG8_MMA(ai, bj, At, Bt) do { __builtin_amdgcn_s_setprio(1); _Pragma("unroll") for (int m = 0; m < 4; ++m) _Pragma("unroll") for (int n = 0; n < 2; ++n) _Pragma("unroll") for (int k = 0; k < 2; ++k) \
;         acc[ai][bj][m][n] = __builtin_amdgcn_mfma_f32_16x16x32_bf16(Bt[n][k], At[m][k], acc[ai][bj][m][n], 0, 0, 0); __builtin_amdgcn_s_setprio(0); } while (0)
; #define PG8_WAIT_V(n) asm volatile("s_waitcnt vmcnt(" #n ")" ::: "memory")
; #define PG8_WAIT_L(n) asm volatile("s_waitcnt lgkmcnt(" #n ")" ::: "memory")
; #define PG8_BAR __builtin_amdgcn_s_barrier()
; #define PG8_SCHED __builtin_amdgcn_sched_barrier(0)
; template <class Epi, class Sched>
; __device__ __forceinline__ void gemm_phase(PG8_LAS unsigned char* lds, const Gemm g, const Sched& S, const Epi& E) {
;     ...
;             PG8_LDA(At, 1, 1); PG8_STAGE(PG8_SB(1, 0), b3, voffB); PG8_STAGE(PG8_SB(1, 1), b3 + hstepB, voffB); PG8_STAGE(PG8_SA(1, 0), a3, voffA);
;             PG8_WAIT_V(8); PG8_WAIT_L(0); PG8_BAR; PG8_MMA(1, 0, At, B0); PG8_MMA(1, 1, At, B1); PG8_BAR; PG8_SCHED;
;         }
;         if (wr == 0) PG8_BAR;
	s_add_i32 s41, s41, s59
	v_lshl_add_u64 v[164:165], v[164:165], 0, s[20:21]
	s_mov_b32 m0, s41
	ds_read_b128 v[178:181], v169 offset:49152
	ds_read_b128 v[182:185], v169 offset:50176
	ds_read_b128 v[186:189], v169 offset:51200
	ds_read_b128 v[190:193], v169 offset:52224
	ds_read_b128 v[202:205], v169 offset:53248
	ds_read_b128 v[206:209], v169 offset:54272
	ds_read_b128 v[210:213], v169 offset:55296
	ds_read_b128 v[214:217], v169 offset:56320
	global_load_lds_dwordx4 v[164:165], off
	s_add_i32 m0, s41, 0x2000
	s_add_u32 s52, s52, 0x10080
	v_lshl_add_u64 v[164:165], v[194:195], 0, s[20:21]
	s_addc_u32 s53, s53, 0
	s_add_i32 s41, s49, s59
	global_load_lds_dwordx4 v[164:165], off
	v_lshl_add_u64 v[164:165], s[52:53], 0, v[0:1]
	s_mov_b32 m0, s41
	s_nop 0
	global_load_lds_dwordx4 v[164:165], off
	v_lshl_add_u64 v[164:165], s[52:53], 0, v[150:151]
	s_add_i32 m0, s41, 0x2000
	s_nop 0
	global_load_lds_dwordx4 v[164:165], off
	v_lshl_add_u64 v[164:165], v[196:197], 0, s[20:21]
	s_mov_b32 m0, s66
	s_nop 0
	global_load_lds_dwordx4 v[164:165], off
	v_lshl_add_u64 v[164:165], v[218:219], 0, s[20:21]
	s_mov_b32 m0, s67
	s_nop 0
	global_load_lds_dwordx4 v[164:165], off
	s_waitcnt vmcnt(8)
	s_waitcnt lgkmcnt(0)
	s_barrier
	s_setprio 0
	s_waitcnt lgkmcnt(0)
	v_mfma_f32_16x16x32_bf16 v[94:97], v[130:133], v[178:181], v[94:97]
	v_mfma_f32_16x16x32_bf16 v[90:93], v[138:141], v[178:181], v[90:93]
	v_mfma_f32_16x16x32_bf16 v[86:89], v[130:133], v[186:189], v[86:89]
	v_mfma_f32_16x16x32_bf16 v[82:85], v[138:141], v[186:189], v[82:85]
	v_mfma_f32_16x16x32_bf16 v[78:81], v[130:133], v[202:205], v[78:81]
	v_mfma_f32_16x16x32_bf16 v[74:77], v[138:141], v[202:205], v[74:77]
	v_mfma_f32_16x16x32_bf16 v[70:73], v[130:133], v[210:213], v[70:73]
	v_mfma_f32_16x16x32_bf16 v[66:69], v[138:141], v[210:213], v[66:69]
	v_mfma_f32_16x16x32_bf16 v[94:97], v[134:137], v[182:185], v[94:97]
	v_mfma_f32_16x16x32_bf16 v[90:93], v[142:145], v[182:185], v[90:93]
	v_mfma_f32_16x16x32_bf16 v[86:89], v[134:137], v[190:193], v[86:89]
	v_mfma_f32_16x16x32_bf16 v[82:85], v[142:145], v[190:193], v[82:85]
	v_mfma_f32_16x16x32_bf16 v[78:81], v[134:137], v[206:209], v[78:81]
	v_mfma_f32_16x16x32_bf16 v[74:77], v[142:145], v[206:209], v[74:77]
	v_mfma_f32_16x16x32_bf16 v[70:73], v[134:137], v[214:217], v[70:73]
	v_mfma_f32_16x16x32_bf16 v[66:69], v[142:145], v[214:217], v[66:69]
	s_setprio 1
	s_setprio 0
	v_mfma_f32_16x16x32_bf16 v[30:33], v[156:159], v[178:181], v[30:33]
	v_mfma_f32_16x16x32_bf16 v[26:29], v[170:173], v[178:181], v[26:29]
	v_mfma_f32_16x16x32_bf16 v[22:25], v[156:159], v[186:189], v[22:25]
	v_mfma_f32_16x16x32_bf16 v[18:21], v[170:173], v[186:189], v[18:21]
	v_mfma_f32_16x16x32_bf16 v[14:17], v[156:159], v[202:205], v[14:17]
	v_mfma_f32_16x16x32_bf16 v[10:13], v[170:173], v[202:205], v[10:13]
	v_mfma_f32_16x16x32_bf16 v[6:9], v[156:159], v[210:213], v[6:9]
	v_mfma_f32_16x16x32_bf16 v[2:5], v[170:173], v[210:213], v[2:5]
	v_mfma_f32_16x16x32_bf16 v[30:33], v[160:163], v[182:185], v[30:33]
	v_mfma_f32_16x16x32_bf16 v[26:29], v[174:177], v[182:185], v[26:29]
	v_mfma_f32_16x16x32_bf16 v[22:25], v[160:163], v[190:193], v[22:25]
	v_mfma_f32_16x16x32_bf16 v[18:21], v[174:177], v[190:193], v[18:21]
	v_mfma_f32_16x16x32_bf16 v[14:17], v[160:163], v[206:209], v[14:17]
	v_mfma_f32_16x16x32_bf16 v[10:13], v[174:177], v[206:209], v[10:13]
	v_mfma_f32_16x16x32_bf16 v[6:9], v[160:163], v[214:217], v[6:9]
	v_mfma_f32_16x16x32_bf16 v[2:5], v[174:177], v[214:217], v[2:5]
	s_setprio 1
	s_barrier
	s_add_i32 s39, s39, 2
	s_add_u32 s6, s6, 0x100
	s_addc_u32 s7, s7, 0
	s_add_u32 s2, s2, 0x100
	s_addc_u32 s18, s18, 0
	s_cmp_gt_u32 s39, 13
	s_cbranch_scc0 .LBB0_161
	s_setprio 0
	s_and_b64 vcc, exec, s[14:15]
	s_cbranch_vccz .LBB0_164
	s_barrier
